# NSA top-k: bisection loops rewritten with scalar threshold/bit and 4 independent compare masks
# speedup vs baseline: 1.0071x; 1.0050x over previous
.LBB0_1104:
	s_or_b64 exec, exec, s[6:7]
	s_and_b64 vcc, exec, s[28:29]
	s_mov_b64 s[6:7], -1
	s_cbranch_vccnz .LBB0_1122
	s_mov_b64 s[52:53], 0
	s_mov_b32 s54, 0
	s_mov_b32 s55, 0x40000000
.Ltk_loop_a:
	s_or_b32 s6, s54, s55
	v_cmp_le_u32_e64 s[56:57], s6, v19
	v_cmp_le_u32_e64 s[58:59], s6, v18
	v_cmp_le_u32_e64 s[60:61], s6, v21
	v_cmp_le_u32_e32 vcc, s6, v20
	s_bcnt1_i32_b64 s7, s[56:57]
	s_bcnt1_i32_b64 s13, s[58:59]
	s_add_i32 s13, s13, s7
	s_bcnt1_i32_b64 s7, s[60:61]
	s_add_i32 s13, s13, s7
	s_bcnt1_i32_b64 s7, vcc
	s_add_i32 s13, s13, s7
	s_cmp_ge_u32 s13, 16
	s_cselect_b32 s54, s6, s54
	s_cmp_eq_u32 s13, 16
	s_cbranch_scc1 .Ltk_exact_a
	s_lshr_b32 s55, s55, 1
	s_cmp_lg_u32 s55, 0
	s_cbranch_scc1 .Ltk_loop_a
	s_branch .Ltk_done_a
.Ltk_exact_a:
	s_mov_b64 s[52:53], -1
.Ltk_done_a:
	v_mov_b32_e32 v22, s54

.Ltk_loop_b:
	s_or_b32 s6, s54, s55
	v_cmp_le_u32_e64 s[56:57], s6, v20
	v_cmp_le_u32_e64 s[58:59], s6, v19
	v_cmp_le_u32_e64 s[60:61], s6, v22
	v_cmp_le_u32_e32 vcc, s6, v21
	s_bcnt1_i32_b64 s7, s[56:57]
	s_bcnt1_i32_b64 s14, s[58:59]
	s_add_i32 s14, s14, s7
	s_bcnt1_i32_b64 s7, s[60:61]
	s_add_i32 s14, s14, s7
	s_bcnt1_i32_b64 s7, vcc
	s_add_i32 s14, s14, s7
	s_cmp_ge_u32 s14, 16
	s_cselect_b32 s54, s6, s54
	s_cmp_eq_u32 s14, 16
	s_cbranch_scc1 .Ltk_exact_b
	s_lshr_b32 s55, s55, 1
	s_cmp_lg_u32 s55, 0
	s_cbranch_scc1 .Ltk_loop_b
	s_branch .Ltk_done_b

.Ltk_done_b:
	v_mov_b32_e32 v23, s54
